# merge and out third-round K sharing in both layers; merge-tail weight conversions (w_up, w_down) on the two-tiles-in-flight loop, workgroups 64-255
# speedup vs baseline: 1.0047x; 1.0047x over previous
; __device__ __forceinline__ int opaque_tid(int wv) { asm volatile("" : "+s"(wv)); unsigned z = 0u; asm volatile("" : "+v"(z)); const int l = __builtin_amdgcn_mbcnt_hi(~0u, __builtin_amdgcn_mbcnt_lo(~0u, z)); return (wv << 6) | l; }
; __device__ __forceinline__ void convert_weight(int wv, const float* __restrict__ src, int ldsrc, int Ksrc, bf16_t* dst, int ldd, int koff, int ntn, const float* kscale, int mode, LAS float* tile, int pidx, int pcnt) {
;     const int tid = opaque_tid(wv); const int ntk = Ksrc / 128; const int total = ntn * ntk; const int G = pcnt;
;     const int kk0 = tid >> 4, n4 = (tid & 15) * 4;
;     f32x4 v[4]; float ks[4];
;     auto prefetch = [&](int t) {
;         const int tn = t % ntn, tk = t / ntn; const int n0 = tn * 64, k0 = tk * 128;
;         int scol = n0, nvalid = 64;
;         if (mode == 1) { if (n0 < 5632) scol = n0; else if (n0 < 13312) scol = n0 + 8; else if (n0 == 13312) { scol = 5632; nvalid = 8; } else { scol = 0; nvalid = 0; } }
; #pragma unroll
;         for (int i = 0; i < 4; ++i) { const int kk = kk0 + i * 32; v[i] = (f32x4){0.f, 0.f, 0.f, 0.f};
;             if (n4 < nvalid) v[i] = *(const f32x4*)(src + (size_t)(k0 + kk) * ldsrc + scol + n4);
;             ks[i] = kscale ? kscale[k0 + kk] : 1.0f; }
;     };
;     int t = pidx; int buf = 0;
;     if (t < total) prefetch(t);
.LBB0_3:
	s_or_b64 exec, exec, s[4:5]
	s_mov_b64 s[4:5], s[0:1]
	s_mov_b32 s26, s81
	s_waitcnt lgkmcnt(0)
	s_barrier
	s_mov_b32 s15, s95
	s_cmpk_gt_i32 s26, 0xd3f
	s_cbranch_scc1 .LBB0_61
	v_mbcnt_lo_u32_b32 v10, -1, 0
	v_mbcnt_hi_u32_b32 v10, -1, v10
	v_lshl_or_b32 v10, s95, 6, v10
	v_lshrrev_b32_e32 v11, 4, v10
	v_and_b32_e32 v9, 15, v10
	v_lshlrev_b32_e32 v9, 2, v9
	v_mul_u32_u24_e32 v4, 0x3408, v11
	v_add_u32_e32 v4, v4, v9
	v_lshlrev_b32_e32 v4, 2, v4
	v_lshlrev_b32_e32 v5, 2, v11
	v_mul_u32_u24_e32 v6, 65, v11
	v_add_u32_e32 v6, v6, v9
	v_lshlrev_b32_e32 v6, 2, v6
	v_lshrrev_b32_e32 v7, 3, v10
	v_and_b32_e32 v8, 7, v10
	v_lshlrev_b32_e32 v8, 4, v8
	v_mul_u32_u24_e32 v11, 65, v8
	v_add_u32_e32 v11, v11, v7
	v_lshlrev_b32_e32 v8, 1, v8
	v_mul_u32_u24_e32 v10, 0x1000, v7
	v_add_u32_e32 v8, v10, v8
	v_lshlrev_b32_e32 v7, 2, v11
	s_load_dwordx2 s[4:5], s[0:1], 0x18
	s_load_dwordx2 s[6:7], s[0:1], 0x10
	s_load_dwordx2 s[8:9], s[0:1], 0xa0
	s_waitcnt lgkmcnt(0)
	s_add_u32 s8, s8, 0x23100000
	s_addc_u32 s9, s9, 0
	s_mov_b32 s10, s26
	s_mul_hi_u32 s15, s10, 0x13521d0
	s_mul_i32 s14, s15, 212
	s_sub_u32 s14, s10, s14
	s_lshl_b32 s18, s14, 6
	s_mov_b32 s28, 0
	s_cmp_lt_u32 s14, 88
	s_cbranch_scc1 .Lcv0_cp0
	s_add_u32 s18, s18, 8
	s_cmp_lt_u32 s14, 208
	s_cbranch_scc1 .Lcv0_cp0
	s_movk_i32 s18, 0x1600
	s_mov_b32 s28, 1
	s_cmp_eq_u32 s14, 208
	s_cbranch_scc1 .Lcv0_cp0
	s_mov_b32 s18, 0
	s_mov_b32 s28, 2

; __device__ __forceinline__ unsigned pack2(float lo, float hi) { unsigned r; asm("v_cvt_pk_bf16_f32 %0, %1, %2" : "=v"(r) : "v"(lo), "v"(hi)); return r; }
; __device__ __forceinline__ void convert_weight(int wv, const float* __restrict__ src, int ldsrc, int Ksrc, bf16_t* dst, int ldd, int koff, int ntn, const float* kscale, int mode, LAS float* tile, int pidx, int pcnt) {
;     ...
;         const int tn = t % ntn, tk = t / ntn; const int n0 = tn * 64, k0 = tk * 128;
;         if (t + G < total) prefetch(t + G);
;         { const int n = tid >> 3, k16 = (tid & 7) * 16; u32x4 w0, w1;
;           w0.x = pack2(tl[(k16 + 0) * 65 + n], tl[(k16 + 1) * 65 + n]); w0.y = pack2(tl[(k16 + 2) * 65 + n], tl[(k16 + 3) * 65 + n]);
;           w0.z = pack2(tl[(k16 + 4) * 65 + n], tl[(k16 + 5) * 65 + n]); w0.w = pack2(tl[(k16 + 6) * 65 + n], tl[(k16 + 7) * 65 + n]);
;           w1.x = pack2(tl[(k16 + 8) * 65 + n], tl[(k16 + 9) * 65 + n]); w1.y = pack2(tl[(k16 + 10) * 65 + n], tl[(k16 + 11) * 65 + n]);
;           w1.z = pack2(tl[(k16 + 12) * 65 + n], tl[(k16 + 13) * 65 + n]); w1.w = pack2(tl[(k16 + 14) * 65 + n], tl[(k16 + 15) * 65 + n]);
;           bf16_t* dp = dst + (size_t)(n0 + n) * ldd + koff + k0 + k16; *(u32x4*)dp = w0; *(u32x4*)(dp + 8) = w1; }
;         buf ^= 1;
.Lcv0_na:
	ds_read_b32 v52, v7 offset:0
	ds_read_b32 v53, v7 offset:260
	ds_read_b32 v54, v7 offset:520
	ds_read_b32 v55, v7 offset:780
	ds_read_b32 v56, v7 offset:1040
	ds_read_b32 v57, v7 offset:1300
	ds_read_b32 v58, v7 offset:1560
	ds_read_b32 v59, v7 offset:1820
	ds_read_b32 v60, v7 offset:2080
	ds_read_b32 v61, v7 offset:2340
	ds_read_b32 v62, v7 offset:2600
	ds_read_b32 v63, v7 offset:2860
	ds_read_b32 v64, v7 offset:3120
	ds_read_b32 v65, v7 offset:3380
	ds_read_b32 v66, v7 offset:3640
	ds_read_b32 v67, v7 offset:3900
	s_mul_hi_u32 s15, s10, 0x13521d0
	s_mul_i32 s14, s15, 212
	s_sub_u32 s14, s10, s14
	s_mul_i32 s14, s14, 0x40000
	s_lshl_b32 s15, s15, 8
	s_add_u32 s14, s14, s15
	s_add_u32 s24, s8, s14
	s_addc_u32 s25, s9, 0
	s_waitcnt lgkmcnt(14)
	v_cvt_pk_bf16_f32 v68, v52, v53
	s_waitcnt lgkmcnt(12)
	v_cvt_pk_bf16_f32 v69, v54, v55
	s_waitcnt lgkmcnt(10)
	v_cvt_pk_bf16_f32 v70, v56, v57
	s_waitcnt lgkmcnt(8)
	v_cvt_pk_bf16_f32 v71, v58, v59
	s_waitcnt lgkmcnt(6)
	v_cvt_pk_bf16_f32 v72, v60, v61
	s_waitcnt lgkmcnt(4)
	v_cvt_pk_bf16_f32 v73, v62, v63
	s_waitcnt lgkmcnt(2)
	v_cvt_pk_bf16_f32 v74, v64, v65
	s_waitcnt lgkmcnt(0)
	v_cvt_pk_bf16_f32 v75, v66, v67
	global_store_dwordx4 v8, v[68:71], s[24:25]
	global_store_dwordx4 v8, v[72:75], s[24:25] offset:16
	s_add_u32 s10, s10, 256
	s_cmp_lt_u32 s10, 3392
	s_cbranch_scc0 .Lcv0_end
	s_cmp_eq_u32 s27, 0
	s_cbranch_scc1 .Lcv0_wa
	s_waitcnt vmcnt(10)
	s_branch .Lcv0_xa

; __device__ __forceinline__ unsigned pack2(float lo, float hi) { unsigned r; asm("v_cvt_pk_bf16_f32 %0, %1, %2" : "=v"(r) : "v"(lo), "v"(hi)); return r; }
; __device__ __forceinline__ void convert_weight(int wv, const float* __restrict__ src, int ldsrc, int Ksrc, bf16_t* dst, int ldd, int koff, int ntn, const float* kscale, int mode, LAS float* tile, int pidx, int pcnt) {
;     ...
;         const int tn = t % ntn, tk = t / ntn; const int n0 = tn * 64, k0 = tk * 128;
;         if (t + G < total) prefetch(t + G);
;         { const int n = tid >> 3, k16 = (tid & 7) * 16; u32x4 w0, w1;
;           w0.x = pack2(tl[(k16 + 0) * 65 + n], tl[(k16 + 1) * 65 + n]); w0.y = pack2(tl[(k16 + 2) * 65 + n], tl[(k16 + 3) * 65 + n]);
;           w0.z = pack2(tl[(k16 + 4) * 65 + n], tl[(k16 + 5) * 65 + n]); w0.w = pack2(tl[(k16 + 6) * 65 + n], tl[(k16 + 7) * 65 + n]);
;           w1.x = pack2(tl[(k16 + 8) * 65 + n], tl[(k16 + 9) * 65 + n]); w1.y = pack2(tl[(k16 + 10) * 65 + n], tl[(k16 + 11) * 65 + n]);
;           w1.z = pack2(tl[(k16 + 12) * 65 + n], tl[(k16 + 13) * 65 + n]); w1.w = pack2(tl[(k16 + 14) * 65 + n], tl[(k16 + 15) * 65 + n]);
;           bf16_t* dp = dst + (size_t)(n0 + n) * ldd + koff + k0 + k16; *(u32x4*)dp = w0; *(u32x4*)(dp + 8) = w1; }
;         buf ^= 1;
.Lcv0_nb:
	ds_read_b32 v52, v7 offset:33280
	ds_read_b32 v53, v7 offset:33540
	ds_read_b32 v54, v7 offset:33800
	ds_read_b32 v55, v7 offset:34060
	ds_read_b32 v56, v7 offset:34320
	ds_read_b32 v57, v7 offset:34580
	ds_read_b32 v58, v7 offset:34840
	ds_read_b32 v59, v7 offset:35100
	ds_read_b32 v60, v7 offset:35360
	ds_read_b32 v61, v7 offset:35620
	ds_read_b32 v62, v7 offset:35880
	ds_read_b32 v63, v7 offset:36140
	ds_read_b32 v64, v7 offset:36400
	ds_read_b32 v65, v7 offset:36660
	ds_read_b32 v66, v7 offset:36920
	ds_read_b32 v67, v7 offset:37180
	s_mul_hi_u32 s15, s10, 0x13521d0
	s_mul_i32 s14, s15, 212
	s_sub_u32 s14, s10, s14
	s_mul_i32 s14, s14, 0x40000
	s_lshl_b32 s15, s15, 8
	s_add_u32 s14, s14, s15
	s_add_u32 s24, s8, s14
	s_addc_u32 s25, s9, 0
	s_waitcnt lgkmcnt(14)
	v_cvt_pk_bf16_f32 v68, v52, v53
	s_waitcnt lgkmcnt(12)
	v_cvt_pk_bf16_f32 v69, v54, v55
	s_waitcnt lgkmcnt(10)
	v_cvt_pk_bf16_f32 v70, v56, v57
	s_waitcnt lgkmcnt(8)
	v_cvt_pk_bf16_f32 v71, v58, v59
	s_waitcnt lgkmcnt(6)
	v_cvt_pk_bf16_f32 v72, v60, v61
	s_waitcnt lgkmcnt(4)
	v_cvt_pk_bf16_f32 v73, v62, v63
	s_waitcnt lgkmcnt(2)
	v_cvt_pk_bf16_f32 v74, v64, v65
	s_waitcnt lgkmcnt(0)
	v_cvt_pk_bf16_f32 v75, v66, v67
	global_store_dwordx4 v8, v[68:71], s[24:25]
	global_store_dwordx4 v8, v[72:75], s[24:25] offset:16
	s_add_u32 s10, s10, 256
	s_cmp_lt_u32 s10, 3392
	s_cbranch_scc0 .Lcv0_end
	s_cmp_eq_u32 s27, 0
	s_cbranch_scc1 .Lcv0_wb
	s_waitcnt vmcnt(10)
	s_branch .Lcv0_xb

;     __device__ bool next(int i, Unit& u) const {
;         const long L = (long)i * G + c; if (L >= nwg) return false;
;         int wgid = (int)L; { const int q = nwg / NXCD, r = nwg % NXCD, xcd = wgid % NXCD, off = wgid / NXCD; wgid = (xcd < r ? xcd * (q + 1) : r * (q + 1) + (xcd - r) * q) + off; }
;         const int nig = WGM * nN, gid = wgid / nig, fm = gid * WGM, gsz = (nM - fm) < WGM ? (nM - fm) : WGM;
;         u.pm = fm + ((wgid % nig) % gsz); u.pn = (wgid % nig) / gsz; return true;
;     }
; template <class Epi, int LDA, int LDB, int KK>
; __device__ __forceinline__ void gemm_phase(int wv, LAS unsigned char* lds, const Gemm g, const StaticOrder& S, const Epi& E) {
;     ...
;         const bool has_next = S.next(ui + 1, nxt);
.LBB0_517:
	s_mov_b32 s100, s101
	s_add_i32 s42, s42, 1
	s_mul_i32 s4, s42, s49
	s_mul_hi_u32 s5, s42, s48
	s_add_i32 s5, s5, s4
	s_mul_i32 s4, s42, s48
	s_add_u32 s16, s4, s28
	s_addc_u32 s17, s5, s35
	s_mov_b32 s101, 0
	s_cmp_lt_u32 s16, 0x200
	s_cbranch_scc1 .Lmt_h1
	s_sub_u32 s98, s16, 0x200
	s_lshr_b32 s99, s98, 4
	s_and_b32 s98, s98, 15
	s_add_u32 s16, s98, 0x200
	s_add_u32 s101, s99, 1
	s_cmp_lt_u32 s99, 4
	s_cbranch_scc1 .Lmt_h1
	s_movk_i32 s16, 0x210
	s_mov_b32 s101, 0

; template <class Epi, int LDA, int LDB, int KK>
; __device__ __forceinline__ void gemm_phase(int wv, LAS unsigned char* lds, const Gemm g, const StaticOrder& S, const Epi& E) {
;     ...
;         for (int seg = 0, t = 0; seg < Epi::NSEG; ++seg) {
;           const int tend = Epi::HAS_MID ? (seg == 0 ? Epi::MID1 : (seg == 1 ? Epi::MID2 : nt)) : nt;
;           for (; t < tend; t += 2) {
.LBB0_521:
	s_cmp_eq_u32 s74, 1
	s_cselect_b32 s23, 24, 32
	s_cmp_lg_u32 s74, 0
	s_cselect_b32 s46, s23, 8
	s_cmp_eq_u32 s100, 1
	s_cbranch_scc0 .Lmt_no
	s_cmp_eq_u32 s74, 0
	s_cbranch_scc1 .Lmt_no
	s_cmp_ge_i32 s22, s46
	s_cbranch_scc1 .Lmt_no
	s_cmp_eq_u32 s74, 2
	s_cbranch_scc1 .Lmt_s2
	s_cmp_lg_u32 s95, 0
	s_cbranch_scc1 .Lmt_o_wait
	s_and_b32 s98, s81, 15
	s_lshl_b32 s98, s98, 2
	s_add_u32 s98, s98, 0x201daa80
	s_add_u32 s98, s10, s98
	s_addc_u32 s99, s11, 0
	s_add_u32 s23, s2, 1
	s_mul_i32 s23, s23, 3
	s_mov_b64 exec, 1
	v_mov_b32_e32 v132, 0
.Lmt_poll:
	s_sleep 2
	global_load_dword v133, v132, s[98:99] sc1
	s_waitcnt vmcnt(0)
	v_cmp_gt_u32_e32 vcc, s23, v133
	s_cbranch_vccnz .Lmt_poll
	buffer_inv sc1
	s_waitcnt vmcnt(0)
	s_mov_b64 exec, -1

; #define LAS __attribute__((address_space(3)))
; __device__ __forceinline__ int opaque_tid(int wv) { asm volatile("" : "+s"(wv)); unsigned z = 0u; asm volatile("" : "+v"(z)); const int l = __builtin_amdgcn_mbcnt_hi(~0u, __builtin_amdgcn_mbcnt_lo(~0u, z)); return (wv << 6) | l; }
; __device__ __forceinline__ void convert_weight(int wv, const float* __restrict__ src, int ldsrc, int Ksrc, bf16_t* dst, int ldd, int koff, int ntn, const float* kscale, int mode, LAS float* tile, int pidx, int pcnt) {
;     const int tid = opaque_tid(wv); const int ntk = Ksrc / 128; const int total = ntn * ntk; const int G = pcnt;
;     const int kk0 = tid >> 4, n4 = (tid & 15) * 4;
;     f32x4 v[4]; float ks[4];
;     auto prefetch = [&](int t) {
;         const int tn = t % ntn, tk = t / ntn; const int n0 = tn * 64, k0 = tk * 128;
;         int scol = n0, nvalid = 64;
;         if (mode == 1) { if (n0 < 5632) scol = n0; else if (n0 < 13312) scol = n0 + 8; else if (n0 == 13312) { scol = 5632; nvalid = 8; } else { scol = 0; nvalid = 0; } }
; #pragma unroll
;         for (int i = 0; i < 4; ++i) { const int kk = kk0 + i * 32; v[i] = (f32x4){0.f, 0.f, 0.f, 0.f};
;             if (n4 < nvalid) v[i] = *(const f32x4*)(src + (size_t)(k0 + kk) * ldsrc + scol + n4);
;             ks[i] = kscale ? kscale[k0 + kk] : 1.0f; }
;     };
;     int t = pidx; int buf = 0;
;     if (t < total) prefetch(t);
; __device__ __forceinline__ void convert_layer(int wv, PP P, int L, int mask, LAS float* tile, int pidx, int pcnt) {
;     ...
;     if (mask & 8) convert_weight(wv, P->w_up + (size_t)L * D * NUP, NUP, D, (bf16_t*)(dob + DO_WUP), D, 0, NUP / 64, P->norm_ffn + L * D, 0, tile, pidx, pcnt);
.LBB0_529:
	s_mov_b32 s4, s81
	s_movk_i32 s5, 64
	s_cmp_lt_i32 s4, s5
	s_cselect_b64 s[6:7], -1, 0
	s_or_b64 s[6:7], s[82:83], s[6:7]
	s_and_b64 vcc, exec, s[6:7]
	s_cbranch_vccnz .LBB0_562
	s_mov_b64 s[12:13], s[0:1]
	s_load_dwordx2 s[6:7], s[12:13], 0xa0
	v_readlane_b32 s8, v254, 30
	v_readlane_b32 s9, v254, 31
	s_movk_i32 s5, 64
	s_and_b64 vcc, exec, s[8:9]
	s_sub_i32 s20, s4, s5
	s_cbranch_vccnz .LBB0_554
	s_mov_b32 s4, s95
	v_mov_b32_e32 v0, v3
	s_cmpk_gt_i32 s20, 0xaff
	s_cbranch_scc1 .LBB0_553
	v_mbcnt_lo_u32_b32 v10, -1, 0
	v_mbcnt_hi_u32_b32 v10, -1, v10
	v_lshl_or_b32 v10, s95, 6, v10
	v_lshrrev_b32_e32 v11, 4, v10
	v_and_b32_e32 v9, 15, v10
	v_lshlrev_b32_e32 v9, 2, v9
	v_mul_u32_u24_e32 v4, 0x2c00, v11
	v_add_u32_e32 v4, v4, v9
	v_lshlrev_b32_e32 v4, 2, v4
	v_lshlrev_b32_e32 v5, 2, v11
	v_mul_u32_u24_e32 v6, 65, v11
	v_add_u32_e32 v6, v6, v9
	v_lshlrev_b32_e32 v6, 2, v6
	v_lshrrev_b32_e32 v7, 3, v10
	v_and_b32_e32 v8, 7, v10
	v_lshlrev_b32_e32 v8, 4, v8
	v_mul_u32_u24_e32 v11, 65, v8
	v_add_u32_e32 v11, v11, v7
	v_lshlrev_b32_e32 v8, 1, v8
	v_mul_u32_u24_e32 v10, 0x1000, v7
	v_add_u32_e32 v8, v10, v8
	v_lshlrev_b32_e32 v7, 2, v11
	s_load_dwordx2 s[4:5], s[0:1], 0x70
	s_load_dwordx2 s[6:7], s[0:1], 0x68
	s_load_dwordx2 s[8:9], s[0:1], 0x98
	s_waitcnt lgkmcnt(0)
	s_add_u32 s8, s8, 0x5200000
	s_addc_u32 s9, s9, 0
	s_sub_u32 s10, s81, 64
	s_mul_hi_u32 s15, s10, 0x1745d18
	s_mul_i32 s14, s15, 176
	s_sub_u32 s14, s10, s14
	s_lshl_b32 s18, s14, 6
	s_mov_b32 s28, 0
	s_mul_i32 s19, s15, 0x160000
	s_add_u32 s19, s19, s18
	s_lshl_b32 s19, s19, 2
	s_add_u32 s20, s4, s19
	s_addc_u32 s21, s5, 0
	s_lshl_b32 s19, s15, 9
	s_add_u32 s22, s6, s19
	s_addc_u32 s23, s7, 0
	global_load_dwordx4 v[12:15], v4, s[20:21]
	global_load_dword v28, v5, s[22:23]
	s_add_u32 s20, s20, 0x160000
	s_addc_u32 s21, s21, 0
	global_load_dwordx4 v[16:19], v4, s[20:21]
	global_load_dword v29, v5, s[22:23] offset:128
	s_add_u32 s20, s20, 0x160000
	s_addc_u32 s21, s21, 0
	global_load_dwordx4 v[20:23], v4, s[20:21]
	global_load_dword v30, v5, s[22:23] offset:256
	s_add_u32 s20, s20, 0x160000
	s_addc_u32 s21, s21, 0
	global_load_dwordx4 v[24:27], v4, s[20:21]
	global_load_dword v31, v5, s[22:23] offset:384
	s_add_u32 s11, s10, 192
	s_cmp_lt_u32 s11, 2816
	s_cbranch_scc0 .Lcv3_p1n
	s_mul_hi_u32 s15, s11, 0x1745d18
	s_mul_i32 s14, s15, 176
	s_sub_u32 s14, s11, s14
	s_lshl_b32 s18, s14, 6
	s_mov_b32 s29, 0
	s_mul_i32 s19, s15, 0x160000
	s_add_u32 s19, s19, s18
	s_lshl_b32 s19, s19, 2
	s_add_u32 s20, s4, s19
	s_addc_u32 s21, s5, 0
	s_lshl_b32 s19, s15, 9
	s_add_u32 s22, s6, s19
	s_addc_u32 s23, s7, 0
	global_load_dwordx4 v[32:35], v4, s[20:21]
	global_load_dword v48, v5, s[22:23]
	s_add_u32 s20, s20, 0x160000
	s_addc_u32 s21, s21, 0
	global_load_dwordx4 v[36:39], v4, s[20:21]
	global_load_dword v49, v5, s[22:23] offset:128
	s_add_u32 s20, s20, 0x160000
	s_addc_u32 s21, s21, 0
	global_load_dwordx4 v[40:43], v4, s[20:21]
	global_load_dword v50, v5, s[22:23] offset:256
	s_add_u32 s20, s20, 0x160000
	s_addc_u32 s21, s21, 0
	global_load_dwordx4 v[44:47], v4, s[20:21]
	global_load_dword v51, v5, s[22:23] offset:384
	s_waitcnt vmcnt(8)
	s_branch .Lcv3_loop

; __device__ __forceinline__ unsigned pack2(float lo, float hi) { unsigned r; asm("v_cvt_pk_bf16_f32 %0, %1, %2" : "=v"(r) : "v"(lo), "v"(hi)); return r; }
; __device__ __forceinline__ void convert_weight(int wv, const float* __restrict__ src, int ldsrc, int Ksrc, bf16_t* dst, int ldd, int koff, int ntn, const float* kscale, int mode, LAS float* tile, int pidx, int pcnt) {
;     ...
;         const int tn = t % ntn, tk = t / ntn; const int n0 = tn * 64, k0 = tk * 128;
;         if (t + G < total) prefetch(t + G);
;         { const int n = tid >> 3, k16 = (tid & 7) * 16; u32x4 w0, w1;
;           w0.x = pack2(tl[(k16 + 0) * 65 + n], tl[(k16 + 1) * 65 + n]); w0.y = pack2(tl[(k16 + 2) * 65 + n], tl[(k16 + 3) * 65 + n]);
;           w0.z = pack2(tl[(k16 + 4) * 65 + n], tl[(k16 + 5) * 65 + n]); w0.w = pack2(tl[(k16 + 6) * 65 + n], tl[(k16 + 7) * 65 + n]);
;           w1.x = pack2(tl[(k16 + 8) * 65 + n], tl[(k16 + 9) * 65 + n]); w1.y = pack2(tl[(k16 + 10) * 65 + n], tl[(k16 + 11) * 65 + n]);
;           w1.z = pack2(tl[(k16 + 12) * 65 + n], tl[(k16 + 13) * 65 + n]); w1.w = pack2(tl[(k16 + 14) * 65 + n], tl[(k16 + 15) * 65 + n]);
;           bf16_t* dp = dst + (size_t)(n0 + n) * ldd + koff + k0 + k16; *(u32x4*)dp = w0; *(u32x4*)(dp + 8) = w1; }
;         buf ^= 1;
.Lcv3_na:
	ds_read_b32 v52, v7 offset:0
	ds_read_b32 v53, v7 offset:260
	ds_read_b32 v54, v7 offset:520
	ds_read_b32 v55, v7 offset:780
	ds_read_b32 v56, v7 offset:1040
	ds_read_b32 v57, v7 offset:1300
	ds_read_b32 v58, v7 offset:1560
	ds_read_b32 v59, v7 offset:1820
	ds_read_b32 v60, v7 offset:2080
	ds_read_b32 v61, v7 offset:2340
	ds_read_b32 v62, v7 offset:2600
	ds_read_b32 v63, v7 offset:2860
	ds_read_b32 v64, v7 offset:3120
	ds_read_b32 v65, v7 offset:3380
	ds_read_b32 v66, v7 offset:3640
	ds_read_b32 v67, v7 offset:3900
	s_mul_hi_u32 s15, s10, 0x1745d18
	s_mul_i32 s14, s15, 176
	s_sub_u32 s14, s10, s14
	s_mul_i32 s14, s14, 0x40000
	s_lshl_b32 s15, s15, 8
	s_add_u32 s14, s14, s15
	s_add_u32 s24, s8, s14
	s_addc_u32 s25, s9, 0
	s_waitcnt lgkmcnt(14)
	v_cvt_pk_bf16_f32 v68, v52, v53
	s_waitcnt lgkmcnt(12)
	v_cvt_pk_bf16_f32 v69, v54, v55
	s_waitcnt lgkmcnt(10)
	v_cvt_pk_bf16_f32 v70, v56, v57
	s_waitcnt lgkmcnt(8)
	v_cvt_pk_bf16_f32 v71, v58, v59
	s_waitcnt lgkmcnt(6)
	v_cvt_pk_bf16_f32 v72, v60, v61
	s_waitcnt lgkmcnt(4)
	v_cvt_pk_bf16_f32 v73, v62, v63
	s_waitcnt lgkmcnt(2)
	v_cvt_pk_bf16_f32 v74, v64, v65
	s_waitcnt lgkmcnt(0)
	v_cvt_pk_bf16_f32 v75, v66, v67
	global_store_dwordx4 v8, v[68:71], s[24:25]
	global_store_dwordx4 v8, v[72:75], s[24:25] offset:16
	s_add_u32 s10, s10, 192
	s_cmp_lt_u32 s10, 2816
	s_cbranch_scc0 .Lcv3_end
	s_cmp_eq_u32 s27, 0
	s_cbranch_scc1 .Lcv3_wa
	s_waitcnt vmcnt(10)
	s_branch .Lcv3_xa

; __device__ __forceinline__ unsigned pack2(float lo, float hi) { unsigned r; asm("v_cvt_pk_bf16_f32 %0, %1, %2" : "=v"(r) : "v"(lo), "v"(hi)); return r; }
; __device__ __forceinline__ void convert_weight(int wv, const float* __restrict__ src, int ldsrc, int Ksrc, bf16_t* dst, int ldd, int koff, int ntn, const float* kscale, int mode, LAS float* tile, int pidx, int pcnt) {
;     ...
;         const int tn = t % ntn, tk = t / ntn; const int n0 = tn * 64, k0 = tk * 128;
;         if (t + G < total) prefetch(t + G);
;         { const int n = tid >> 3, k16 = (tid & 7) * 16; u32x4 w0, w1;
;           w0.x = pack2(tl[(k16 + 0) * 65 + n], tl[(k16 + 1) * 65 + n]); w0.y = pack2(tl[(k16 + 2) * 65 + n], tl[(k16 + 3) * 65 + n]);
;           w0.z = pack2(tl[(k16 + 4) * 65 + n], tl[(k16 + 5) * 65 + n]); w0.w = pack2(tl[(k16 + 6) * 65 + n], tl[(k16 + 7) * 65 + n]);
;           w1.x = pack2(tl[(k16 + 8) * 65 + n], tl[(k16 + 9) * 65 + n]); w1.y = pack2(tl[(k16 + 10) * 65 + n], tl[(k16 + 11) * 65 + n]);
;           w1.z = pack2(tl[(k16 + 12) * 65 + n], tl[(k16 + 13) * 65 + n]); w1.w = pack2(tl[(k16 + 14) * 65 + n], tl[(k16 + 15) * 65 + n]);
;           bf16_t* dp = dst + (size_t)(n0 + n) * ldd + koff + k0 + k16; *(u32x4*)dp = w0; *(u32x4*)(dp + 8) = w1; }
;         buf ^= 1;
.Lcv3_nb:
	ds_read_b32 v52, v7 offset:33280
	ds_read_b32 v53, v7 offset:33540
	ds_read_b32 v54, v7 offset:33800
	ds_read_b32 v55, v7 offset:34060
	ds_read_b32 v56, v7 offset:34320
	ds_read_b32 v57, v7 offset:34580
	ds_read_b32 v58, v7 offset:34840
	ds_read_b32 v59, v7 offset:35100
	ds_read_b32 v60, v7 offset:35360
	ds_read_b32 v61, v7 offset:35620
	ds_read_b32 v62, v7 offset:35880
	ds_read_b32 v63, v7 offset:36140
	ds_read_b32 v64, v7 offset:36400
	ds_read_b32 v65, v7 offset:36660
	ds_read_b32 v66, v7 offset:36920
	ds_read_b32 v67, v7 offset:37180
	s_mul_hi_u32 s15, s10, 0x1745d18
	s_mul_i32 s14, s15, 176
	s_sub_u32 s14, s10, s14
	s_mul_i32 s14, s14, 0x40000
	s_lshl_b32 s15, s15, 8
	s_add_u32 s14, s14, s15
	s_add_u32 s24, s8, s14
	s_addc_u32 s25, s9, 0
	s_waitcnt lgkmcnt(14)
	v_cvt_pk_bf16_f32 v68, v52, v53
	s_waitcnt lgkmcnt(12)
	v_cvt_pk_bf16_f32 v69, v54, v55
	s_waitcnt lgkmcnt(10)
	v_cvt_pk_bf16_f32 v70, v56, v57
	s_waitcnt lgkmcnt(8)
	v_cvt_pk_bf16_f32 v71, v58, v59
	s_waitcnt lgkmcnt(6)
	v_cvt_pk_bf16_f32 v72, v60, v61
	s_waitcnt lgkmcnt(4)
	v_cvt_pk_bf16_f32 v73, v62, v63
	s_waitcnt lgkmcnt(2)
	v_cvt_pk_bf16_f32 v74, v64, v65
	s_waitcnt lgkmcnt(0)
	v_cvt_pk_bf16_f32 v75, v66, v67
	global_store_dwordx4 v8, v[68:71], s[24:25]
	global_store_dwordx4 v8, v[72:75], s[24:25] offset:16
	s_add_u32 s10, s10, 192
	s_cmp_lt_u32 s10, 2816
	s_cbranch_scc0 .Lcv3_end
	s_cmp_eq_u32 s27, 0
	s_cbranch_scc1 .Lcv3_wb
	s_waitcnt vmcnt(10)
	s_branch .Lcv3_xb

; #define LAS __attribute__((address_space(3)))
; __device__ __forceinline__ PP get_params() { unsigned long long kp = (unsigned long long)__builtin_amdgcn_kernarg_segment_ptr(); asm volatile("" : "+s"(kp)); return (PP)kp; }
; __device__ __forceinline__ int opaque_bid() { int t = blockIdx.x; asm volatile("" : "+s"(t)); return t; }
; __device__ __forceinline__ void fill_convert(int wv, LAS unsigned char* lds, int nunits, int L, int mask) {
;     const int G = (int)gridDim.x, extra = nunits % G, bid = opaque_bid();
;     if (extra != 0 && bid >= extra) convert_layer(wv, get_params(), L, mask, (LAS float*)lds, bid - extra, G - extra);
.Lcv3_end:
	s_sub_u32 s20, s81, 64

; #define LAS __attribute__((address_space(3)))
; __device__ __forceinline__ int opaque_tid(int wv) { asm volatile("" : "+s"(wv)); unsigned z = 0u; asm volatile("" : "+v"(z)); const int l = __builtin_amdgcn_mbcnt_hi(~0u, __builtin_amdgcn_mbcnt_lo(~0u, z)); return (wv << 6) | l; }
; __device__ __forceinline__ void convert_weight(int wv, const float* __restrict__ src, int ldsrc, int Ksrc, bf16_t* dst, int ldd, int koff, int ntn, const float* kscale, int mode, LAS float* tile, int pidx, int pcnt) {
;     const int tid = opaque_tid(wv); const int ntk = Ksrc / 128; const int total = ntn * ntk; const int G = pcnt;
;     const int kk0 = tid >> 4, n4 = (tid & 15) * 4;
;     f32x4 v[4]; float ks[4];
;     auto prefetch = [&](int t) {
;         const int tn = t % ntn, tk = t / ntn; const int n0 = tn * 64, k0 = tk * 128;
;         int scol = n0, nvalid = 64;
;         if (mode == 1) { if (n0 < 5632) scol = n0; else if (n0 < 13312) scol = n0 + 8; else if (n0 == 13312) { scol = 5632; nvalid = 8; } else { scol = 0; nvalid = 0; } }
; #pragma unroll
;         for (int i = 0; i < 4; ++i) { const int kk = kk0 + i * 32; v[i] = (f32x4){0.f, 0.f, 0.f, 0.f};
;             if (n4 < nvalid) v[i] = *(const f32x4*)(src + (size_t)(k0 + kk) * ldsrc + scol + n4);
;             ks[i] = kscale ? kscale[k0 + kk] : 1.0f; }
;     };
;     int t = pidx; int buf = 0;
;     if (t < total) prefetch(t);
; __device__ __forceinline__ void convert_layer(int wv, PP P, int L, int mask, LAS float* tile, int pidx, int pcnt) {
;     ...
;     if (mask & 16) convert_weight(wv, P->w_down + (size_t)L * DFF * D, D, DFF, (bf16_t*)(ws + WS_WDOWN), DFF, 0, D / 64, nullptr, 0, tile, pidx, pcnt);
.LBB0_554:
	s_mov_b32 s8, s95
	s_waitcnt vmcnt(0)
	v_mov_b32_e32 v0, v3
	s_cmpk_gt_i32 s20, 0x57f
	s_cbranch_scc1 .LBB0_561
	v_mbcnt_lo_u32_b32 v10, -1, 0
	v_mbcnt_hi_u32_b32 v10, -1, v10
	v_lshl_or_b32 v10, s95, 6, v10
	v_lshrrev_b32_e32 v11, 4, v10
	v_and_b32_e32 v9, 15, v10
	v_lshlrev_b32_e32 v9, 2, v9
	v_mul_u32_u24_e32 v4, 0x800, v11
	v_add_u32_e32 v4, v4, v9
	v_lshlrev_b32_e32 v4, 2, v4
	v_lshlrev_b32_e32 v5, 2, v11
	v_mul_u32_u24_e32 v6, 65, v11
	v_add_u32_e32 v6, v6, v9
	v_lshlrev_b32_e32 v6, 2, v6
	v_lshrrev_b32_e32 v7, 3, v10
	v_and_b32_e32 v8, 7, v10
	v_lshlrev_b32_e32 v8, 4, v8
	v_mul_u32_u24_e32 v11, 65, v8
	v_add_u32_e32 v11, v11, v7
	v_lshlrev_b32_e32 v8, 1, v8
	v_mul_u32_u24_e32 v10, 0x2c00, v7
	v_add_u32_e32 v8, v10, v8
	v_lshlrev_b32_e32 v7, 2, v11
	s_load_dwordx2 s[4:5], s[0:1], 0x88
	s_load_dwordx2 s[8:9], s[0:1], 0xa0
	s_waitcnt lgkmcnt(0)
	s_mul_i32 s19, s2, 0x2c00000
	s_add_u32 s4, s4, s19
	s_addc_u32 s5, s5, 0
	s_add_u32 s8, s8, 0x26600000
	s_addc_u32 s9, s9, 0
	s_sub_u32 s10, s81, 64
	s_mul_hi_u32 s15, s10, 0x8000000
	s_mul_i32 s14, s15, 32
	s_sub_u32 s14, s10, s14
	s_lshl_b32 s18, s14, 6
	s_mov_b32 s28, 0
	s_mul_i32 s19, s15, 0x40000
	s_add_u32 s19, s19, s18
	s_lshl_b32 s19, s19, 2
	s_add_u32 s20, s4, s19
	s_addc_u32 s21, s5, 0
	global_load_dwordx4 v[12:15], v4, s[20:21]
	s_add_u32 s20, s20, 0x40000
	s_addc_u32 s21, s21, 0
	global_load_dwordx4 v[16:19], v4, s[20:21]
	s_add_u32 s20, s20, 0x40000
	s_addc_u32 s21, s21, 0
	global_load_dwordx4 v[20:23], v4, s[20:21]
	s_add_u32 s20, s20, 0x40000
	s_addc_u32 s21, s21, 0
	global_load_dwordx4 v[24:27], v4, s[20:21]
	s_add_u32 s11, s10, 192
	s_cmp_lt_u32 s11, 1408
	s_cbranch_scc0 .Lcv4_p1n
	s_mul_hi_u32 s15, s11, 0x8000000
	s_mul_i32 s14, s15, 32
	s_sub_u32 s14, s11, s14
	s_lshl_b32 s18, s14, 6
	s_mov_b32 s29, 0
	s_mul_i32 s19, s15, 0x40000
	s_add_u32 s19, s19, s18
	s_lshl_b32 s19, s19, 2
	s_add_u32 s20, s4, s19
	s_addc_u32 s21, s5, 0
	global_load_dwordx4 v[32:35], v4, s[20:21]
	s_add_u32 s20, s20, 0x40000
	s_addc_u32 s21, s21, 0
	global_load_dwordx4 v[36:39], v4, s[20:21]
	s_add_u32 s20, s20, 0x40000
	s_addc_u32 s21, s21, 0
	global_load_dwordx4 v[40:43], v4, s[20:21]
	s_add_u32 s20, s20, 0x40000
	s_addc_u32 s21, s21, 0
	global_load_dwordx4 v[44:47], v4, s[20:21]
	s_waitcnt vmcnt(4)
	s_branch .Lcv4_loop

; #define LAS __attribute__((address_space(3)))
; __device__ __forceinline__ void lds_barrier() { asm volatile("s_waitcnt lgkmcnt(0)" ::: "memory"); __builtin_amdgcn_s_barrier(); asm volatile("" ::: "memory"); }
; __device__ __forceinline__ unsigned pack2(float lo, float hi) { unsigned r; asm("v_cvt_pk_bf16_f32 %0, %1, %2" : "=v"(r) : "v"(lo), "v"(hi)); return r; }
; __device__ __forceinline__ void convert_weight(int wv, const float* __restrict__ src, int ldsrc, int Ksrc, bf16_t* dst, int ldd, int koff, int ntn, const float* kscale, int mode, LAS float* tile, int pidx, int pcnt) {
;     ...
;     for (; t < total; t += G) {
;         LAS float* tl = tile + buf * (128 * 65);
; #pragma unroll
;         for (int i = 0; i < 4; ++i) { const int kk = kk0 + i * 32;
;             tl[kk * 65 + n4 + 0] = v[i][0] * ks[i]; tl[kk * 65 + n4 + 1] = v[i][1] * ks[i]; tl[kk * 65 + n4 + 2] = v[i][2] * ks[i]; tl[kk * 65 + n4 + 3] = v[i][3] * ks[i]; }
;         lds_barrier();
;         const int tn = t % ntn, tk = t / ntn; const int n0 = tn * 64, k0 = tk * 128;
;         if (t + G < total) prefetch(t + G);
;         { const int n = tid >> 3, k16 = (tid & 7) * 16; u32x4 w0, w1;
;           w0.x = pack2(tl[(k16 + 0) * 65 + n], tl[(k16 + 1) * 65 + n]); w0.y = pack2(tl[(k16 + 2) * 65 + n], tl[(k16 + 3) * 65 + n]);
;           w0.z = pack2(tl[(k16 + 4) * 65 + n], tl[(k16 + 5) * 65 + n]); w0.w = pack2(tl[(k16 + 6) * 65 + n], tl[(k16 + 7) * 65 + n]);
;           w1.x = pack2(tl[(k16 + 8) * 65 + n], tl[(k16 + 9) * 65 + n]); w1.y = pack2(tl[(k16 + 10) * 65 + n], tl[(k16 + 11) * 65 + n]);
;           w1.z = pack2(tl[(k16 + 12) * 65 + n], tl[(k16 + 13) * 65 + n]); w1.w = pack2(tl[(k16 + 14) * 65 + n], tl[(k16 + 15) * 65 + n]);
;           bf16_t* dp = dst + (size_t)(n0 + n) * ldd + koff + k0 + k16; *(u32x4*)dp = w0; *(u32x4*)(dp + 8) = w1; }
;         buf ^= 1;
.Lcv4_loop:
	ds_write_b32 v6, v12 offset:0
	ds_write_b32 v6, v13 offset:4
	ds_write_b32 v6, v14 offset:8
	ds_write_b32 v6, v15 offset:12
	ds_write_b32 v6, v16 offset:8320
	ds_write_b32 v6, v17 offset:8324
	ds_write_b32 v6, v18 offset:8328
	ds_write_b32 v6, v19 offset:8332
	ds_write_b32 v6, v20 offset:16640
	ds_write_b32 v6, v21 offset:16644
	ds_write_b32 v6, v22 offset:16648
	ds_write_b32 v6, v23 offset:16652
	ds_write_b32 v6, v24 offset:24960
	ds_write_b32 v6, v25 offset:24964
	ds_write_b32 v6, v26 offset:24968
	ds_write_b32 v6, v27 offset:24972
	s_waitcnt lgkmcnt(0)
	s_barrier
	s_add_u32 s11, s10, 384
	s_mov_b32 s27, 0
	s_cmp_lt_u32 s11, 1408
	s_cbranch_scc0 .Lcv4_na
	s_mov_b32 s27, 1
	s_mul_hi_u32 s15, s11, 0x8000000
	s_mul_i32 s14, s15, 32
	s_sub_u32 s14, s11, s14
	s_lshl_b32 s18, s14, 6
	s_mov_b32 s28, 0
	s_mul_i32 s19, s15, 0x40000
	s_add_u32 s19, s19, s18
	s_lshl_b32 s19, s19, 2
	s_add_u32 s20, s4, s19
	s_addc_u32 s21, s5, 0
	global_load_dwordx4 v[12:15], v4, s[20:21]
	s_add_u32 s20, s20, 0x40000
	s_addc_u32 s21, s21, 0
	global_load_dwordx4 v[16:19], v4, s[20:21]
	s_add_u32 s20, s20, 0x40000
	s_addc_u32 s21, s21, 0
	global_load_dwordx4 v[20:23], v4, s[20:21]
	s_add_u32 s20, s20, 0x40000
	s_addc_u32 s21, s21, 0
	global_load_dwordx4 v[24:27], v4, s[20:21]
.Lcv4_na:
	ds_read_b32 v52, v7 offset:0
	ds_read_b32 v53, v7 offset:260
	ds_read_b32 v54, v7 offset:520
	ds_read_b32 v55, v7 offset:780
	ds_read_b32 v56, v7 offset:1040
	ds_read_b32 v57, v7 offset:1300
	ds_read_b32 v58, v7 offset:1560
	ds_read_b32 v59, v7 offset:1820
	ds_read_b32 v60, v7 offset:2080
	ds_read_b32 v61, v7 offset:2340
	ds_read_b32 v62, v7 offset:2600
	ds_read_b32 v63, v7 offset:2860
	ds_read_b32 v64, v7 offset:3120
	ds_read_b32 v65, v7 offset:3380
	ds_read_b32 v66, v7 offset:3640
	ds_read_b32 v67, v7 offset:3900
	s_mul_hi_u32 s15, s10, 0x8000000
	s_mul_i32 s14, s15, 32
	s_sub_u32 s14, s10, s14
	s_mul_i32 s14, s14, 0xb0000
	s_lshl_b32 s15, s15, 8
	s_add_u32 s14, s14, s15
	s_add_u32 s24, s8, s14
	s_addc_u32 s25, s9, 0
	s_waitcnt lgkmcnt(14)
	v_cvt_pk_bf16_f32 v68, v52, v53
	s_waitcnt lgkmcnt(12)
	v_cvt_pk_bf16_f32 v69, v54, v55
	s_waitcnt lgkmcnt(10)
	v_cvt_pk_bf16_f32 v70, v56, v57
	s_waitcnt lgkmcnt(8)
	v_cvt_pk_bf16_f32 v71, v58, v59
	s_waitcnt lgkmcnt(6)
	v_cvt_pk_bf16_f32 v72, v60, v61
	s_waitcnt lgkmcnt(4)
	v_cvt_pk_bf16_f32 v73, v62, v63
	s_waitcnt lgkmcnt(2)
	v_cvt_pk_bf16_f32 v74, v64, v65
	s_waitcnt lgkmcnt(0)
	v_cvt_pk_bf16_f32 v75, v66, v67
	global_store_dwordx4 v8, v[68:71], s[24:25]
	global_store_dwordx4 v8, v[72:75], s[24:25] offset:16
	s_add_u32 s10, s10, 192
	s_cmp_lt_u32 s10, 1408
	s_cbranch_scc0 .Lcv4_end
	s_cmp_eq_u32 s27, 0
	s_cbranch_scc1 .Lcv4_wa
	s_waitcnt vmcnt(6)
	s_branch .Lcv4_xa

; #define LAS __attribute__((address_space(3)))
; __device__ __forceinline__ void lds_barrier() { asm volatile("s_waitcnt lgkmcnt(0)" ::: "memory"); __builtin_amdgcn_s_barrier(); asm volatile("" ::: "memory"); }
; __device__ __forceinline__ unsigned pack2(float lo, float hi) { unsigned r; asm("v_cvt_pk_bf16_f32 %0, %1, %2" : "=v"(r) : "v"(lo), "v"(hi)); return r; }
; __device__ __forceinline__ void convert_weight(int wv, const float* __restrict__ src, int ldsrc, int Ksrc, bf16_t* dst, int ldd, int koff, int ntn, const float* kscale, int mode, LAS float* tile, int pidx, int pcnt) {
;     ...
;     for (; t < total; t += G) {
;         LAS float* tl = tile + buf * (128 * 65);
; #pragma unroll
;         for (int i = 0; i < 4; ++i) { const int kk = kk0 + i * 32;
;             tl[kk * 65 + n4 + 0] = v[i][0] * ks[i]; tl[kk * 65 + n4 + 1] = v[i][1] * ks[i]; tl[kk * 65 + n4 + 2] = v[i][2] * ks[i]; tl[kk * 65 + n4 + 3] = v[i][3] * ks[i]; }
;         lds_barrier();
;         const int tn = t % ntn, tk = t / ntn; const int n0 = tn * 64, k0 = tk * 128;
;         if (t + G < total) prefetch(t + G);
;         { const int n = tid >> 3, k16 = (tid & 7) * 16; u32x4 w0, w1;
;           w0.x = pack2(tl[(k16 + 0) * 65 + n], tl[(k16 + 1) * 65 + n]); w0.y = pack2(tl[(k16 + 2) * 65 + n], tl[(k16 + 3) * 65 + n]);
;           w0.z = pack2(tl[(k16 + 4) * 65 + n], tl[(k16 + 5) * 65 + n]); w0.w = pack2(tl[(k16 + 6) * 65 + n], tl[(k16 + 7) * 65 + n]);
;           w1.x = pack2(tl[(k16 + 8) * 65 + n], tl[(k16 + 9) * 65 + n]); w1.y = pack2(tl[(k16 + 10) * 65 + n], tl[(k16 + 11) * 65 + n]);
;           w1.z = pack2(tl[(k16 + 12) * 65 + n], tl[(k16 + 13) * 65 + n]); w1.w = pack2(tl[(k16 + 14) * 65 + n], tl[(k16 + 15) * 65 + n]);
;           bf16_t* dp = dst + (size_t)(n0 + n) * ldd + koff + k0 + k16; *(u32x4*)dp = w0; *(u32x4*)(dp + 8) = w1; }
;         buf ^= 1;
.Lcv4_xa:
	ds_write_b32 v6, v32 offset:33280
	ds_write_b32 v6, v33 offset:33284
	ds_write_b32 v6, v34 offset:33288
	ds_write_b32 v6, v35 offset:33292
	ds_write_b32 v6, v36 offset:41600
	ds_write_b32 v6, v37 offset:41604
	ds_write_b32 v6, v38 offset:41608
	ds_write_b32 v6, v39 offset:41612
	ds_write_b32 v6, v40 offset:49920
	ds_write_b32 v6, v41 offset:49924
	ds_write_b32 v6, v42 offset:49928
	ds_write_b32 v6, v43 offset:49932
	ds_write_b32 v6, v44 offset:58240
	ds_write_b32 v6, v45 offset:58244
	ds_write_b32 v6, v46 offset:58248
	ds_write_b32 v6, v47 offset:58252
	s_waitcnt lgkmcnt(0)
	s_barrier
	s_add_u32 s11, s10, 384
	s_mov_b32 s27, 0
	s_cmp_lt_u32 s11, 1408
	s_cbranch_scc0 .Lcv4_nb
	s_mov_b32 s27, 1
	s_mul_hi_u32 s15, s11, 0x8000000
	s_mul_i32 s14, s15, 32
	s_sub_u32 s14, s11, s14
	s_lshl_b32 s18, s14, 6
	s_mov_b32 s29, 0
	s_mul_i32 s19, s15, 0x40000
	s_add_u32 s19, s19, s18
	s_lshl_b32 s19, s19, 2
	s_add_u32 s20, s4, s19
	s_addc_u32 s21, s5, 0
	global_load_dwordx4 v[32:35], v4, s[20:21]
	s_add_u32 s20, s20, 0x40000
	s_addc_u32 s21, s21, 0
	global_load_dwordx4 v[36:39], v4, s[20:21]
	s_add_u32 s20, s20, 0x40000
	s_addc_u32 s21, s21, 0
	global_load_dwordx4 v[40:43], v4, s[20:21]
	s_add_u32 s20, s20, 0x40000
	s_addc_u32 s21, s21, 0
	global_load_dwordx4 v[44:47], v4, s[20:21]
.Lcv4_nb:
	ds_read_b32 v52, v7 offset:33280
	ds_read_b32 v53, v7 offset:33540
	ds_read_b32 v54, v7 offset:33800
	ds_read_b32 v55, v7 offset:34060
	ds_read_b32 v56, v7 offset:34320
	ds_read_b32 v57, v7 offset:34580
	ds_read_b32 v58, v7 offset:34840
	ds_read_b32 v59, v7 offset:35100
	ds_read_b32 v60, v7 offset:35360
	ds_read_b32 v61, v7 offset:35620
	ds_read_b32 v62, v7 offset:35880
	ds_read_b32 v63, v7 offset:36140
	ds_read_b32 v64, v7 offset:36400
	ds_read_b32 v65, v7 offset:36660
	ds_read_b32 v66, v7 offset:36920
	ds_read_b32 v67, v7 offset:37180
	s_mul_hi_u32 s15, s10, 0x8000000
	s_mul_i32 s14, s15, 32
	s_sub_u32 s14, s10, s14
	s_mul_i32 s14, s14, 0xb0000
	s_lshl_b32 s15, s15, 8
	s_add_u32 s14, s14, s15
	s_add_u32 s24, s8, s14
	s_addc_u32 s25, s9, 0
	s_waitcnt lgkmcnt(14)
	v_cvt_pk_bf16_f32 v68, v52, v53
	s_waitcnt lgkmcnt(12)
	v_cvt_pk_bf16_f32 v69, v54, v55
	s_waitcnt lgkmcnt(10)
	v_cvt_pk_bf16_f32 v70, v56, v57
	s_waitcnt lgkmcnt(8)
	v_cvt_pk_bf16_f32 v71, v58, v59
	s_waitcnt lgkmcnt(6)
	v_cvt_pk_bf16_f32 v72, v60, v61
	s_waitcnt lgkmcnt(4)
	v_cvt_pk_bf16_f32 v73, v62, v63
	s_waitcnt lgkmcnt(2)
	v_cvt_pk_bf16_f32 v74, v64, v65
	s_waitcnt lgkmcnt(0)
	v_cvt_pk_bf16_f32 v75, v66, v67
	global_store_dwordx4 v8, v[68:71], s[24:25]
	global_store_dwordx4 v8, v[72:75], s[24:25] offset:16
	s_add_u32 s10, s10, 192
	s_cmp_lt_u32 s10, 1408
	s_cbranch_scc0 .Lcv4_end
	s_cmp_eq_u32 s27, 0
	s_cbranch_scc1 .Lcv4_wb
	s_waitcnt vmcnt(6)
	s_branch .Lcv4_xb

; #define LAS __attribute__((address_space(3)))
; __device__ __forceinline__ PP get_params() { unsigned long long kp = (unsigned long long)__builtin_amdgcn_kernarg_segment_ptr(); asm volatile("" : "+s"(kp)); return (PP)kp; }
; __device__ __forceinline__ int opaque_tid(int wv) { asm volatile("" : "+s"(wv)); unsigned z = 0u; asm volatile("" : "+v"(z)); const int l = __builtin_amdgcn_mbcnt_hi(~0u, __builtin_amdgcn_mbcnt_lo(~0u, z)); return (wv << 6) | l; }
; __device__ __forceinline__ unsigned xb_add(unsigned* p, unsigned v) { return __hip_atomic_fetch_add(p, v, __ATOMIC_RELAXED, __HIP_MEMORY_SCOPE_AGENT); }
; __device__ __forceinline__ unsigned xb_xcc_id() { return (unsigned)__builtin_amdgcn_s_getreg((3 << 11) | 20) & 0xFu; }
; __device__ __forceinline__ void gbar(int wv, LAS unsigned char* lds) {
;     asm volatile("s_waitcnt vmcnt(0)" ::: "memory");
;     __syncthreads();
;     const int tid = opaque_tid(wv); unsigned* bar = (unsigned*)(get_params()->ws + WS_BAR);
;     if (tid == 0) {
;         volatile LAS unsigned* st = (volatile LAS unsigned*)(lds + LDS_ST); const unsigned x = xb_xcc_id();
;         __builtin_amdgcn_s_waitcnt(0);
;         unsigned nloc = st[0], nx = st[1];
;         if (nloc == 0u) { xcd_barrier_complete(bar, x, nloc, nx); st[0] = nloc; st[1] = nx; }
;         const unsigned old = xb_add(&bar[XB_XSUB(x)], 1u);
.Lcv4_end:
.LBB0_561:
	s_waitcnt lgkmcnt(0)
	s_barrier
.LBB0_562:
	s_mov_b32 s4, s95
	v_mov_b32_e32 v0, v3
	s_waitcnt vmcnt(0)
	s_waitcnt lgkmcnt(0)
	s_barrier
	s_mov_b64 s[6:7], s[0:1]
	v_mbcnt_lo_u32_b32 v0, -1, v0
	v_mbcnt_hi_u32_b32 v0, -1, v0
	v_lshl_or_b32 v0, s4, 6, v0
	v_cmp_eq_u32_e32 vcc, 0, v0
	s_and_saveexec_b64 s[4:5], vcc
	s_cbranch_execz .LBB0_614
	v_mov_b32_e32 v0, s88
	s_load_dwordx2 s[6:7], s[6:7], 0xa0
	s_getreg_b32 s8, hwreg(HW_REG_XCC_ID, 0, 4)
	s_waitcnt vmcnt(0) expcnt(0) lgkmcnt(0)
	ds_read_b32 v2, v0
	v_mov_b32_e32 v0, s89
	ds_read_b32 v0, v0
	s_and_b32 s46, s8, 15
	s_waitcnt lgkmcnt(1)
	v_cmp_ne_u32_e32 vcc, 0, v2
	s_cbranch_vccnz .LBB0_578
	s_add_u32 s8, s6, 0x285daa00
	s_addc_u32 s9, s7, 0
	s_add_u32 s10, s6, 0x285dac00
	s_addc_u32 s11, s7, 0
	s_add_u32 s12, s6, 0x285dad00
	s_addc_u32 s13, s7, 0
	s_add_u32 s14, s6, 0x285dae00
	s_addc_u32 s15, s7, 0
	s_add_u32 s16, s6, 0x285daf00
	s_addc_u32 s17, s7, 0
	s_add_u32 s18, s6, 0x285db000
	s_addc_u32 s19, s7, 0
	s_add_u32 s20, s6, 0x285db100
	s_addc_u32 s21, s7, 0
	s_add_u32 s22, s6, 0x285db200
	s_addc_u32 s23, s7, 0
	s_add_u32 s24, s6, 0x285db300
	s_addc_u32 s25, s7, 0
	s_add_u32 s26, s6, 0x285db400
	s_addc_u32 s27, s7, 0
	s_add_u32 s28, s6, 0x285db500
	s_addc_u32 s29, s7, 0
	s_add_u32 s30, s6, 0x285db600
	s_addc_u32 s31, s7, 0
	s_add_u32 s34, s6, 0x285db700
	s_addc_u32 s35, s7, 0
	s_add_u32 s36, s6, 0x285db800
	s_addc_u32 s37, s7, 0
	s_add_u32 s38, s6, 0x285db900
	s_addc_u32 s39, s7, 0
	s_add_u32 s40, s6, 0x285dba00
	s_addc_u32 s41, s7, 0
	s_add_u32 s42, s6, 0x285dbb00
	s_addc_u32 s43, s7, 0
	s_mov_b32 s47, 1
	s_branch .LBB0_566

;     __device__ bool next(int i, Unit& u) const {
;         const long L = (long)i * G + c; if (L >= nwg) return false;
;         int wgid = (int)L; { const int q = nwg / NXCD, r = nwg % NXCD, xcd = wgid % NXCD, off = wgid / NXCD; wgid = (xcd < r ? xcd * (q + 1) : r * (q + 1) + (xcd - r) * q) + off; }
;         const int nig = WGM * nN, gid = wgid / nig, fm = gid * WGM, gsz = (nM - fm) < WGM ? (nM - fm) : WGM;
;         u.pm = fm + ((wgid % nig) % gsz); u.pn = (wgid % nig) / gsz; return true;
;     }
; template <class Epi, int LDA, int LDB, int KK>
; __device__ __forceinline__ void gemm_phase(int wv, LAS unsigned char* lds, const Gemm g, const StaticOrder& S, const Epi& E) {
;     ...
;         const bool has_next = S.next(ui + 1, nxt);
.LBB0_619:
	s_add_i32 s46, s46, 1
	s_mul_i32 s6, s46, s49
	s_mul_hi_u32 s7, s46, s48
	s_add_i32 s7, s7, s6
	s_mul_i32 s6, s46, s48
	s_add_u32 s18, s6, s30
	s_addc_u32 s19, s7, s39
	s_mov_b32 s101, 0
	s_cmp_lt_u32 s18, 0x200
	s_cbranch_scc1 .Lot_h1
	s_sub_u32 s98, s18, 0x200
	s_lshr_b32 s99, s98, 4
	s_and_b32 s98, s98, 15
	s_add_u32 s18, s98, 0x200
	s_add_u32 s101, s99, 1
	s_cmp_lt_u32 s99, 4
	s_cbranch_scc1 .Lot_h1
	s_movk_i32 s18, 0x210
	s_mov_b32 s101, 0

; template <class Epi, int LDA, int LDB, int KK>
; __device__ __forceinline__ void gemm_phase(int wv, LAS unsigned char* lds, const Gemm g, const StaticOrder& S, const Epi& E) {
;     ...
;         for (int seg = 0, t = 0; seg < Epi::NSEG; ++seg) {
;           const int tend = Epi::HAS_MID ? (seg == 0 ? Epi::MID1 : (seg == 1 ? Epi::MID2 : nt)) : nt;
;           for (; t < tend; t += 2) {
.Lot_owner:
	s_cmp_lg_u32 s95, 0
	s_cbranch_scc1 .Lot_o_wait
	s_and_b32 s98, s81, 15
	s_lshl_b32 s98, s98, 2
	s_add_u32 s98, s98, 0x285da940
	s_add_u32 s98, s10, s98
	s_addc_u32 s99, s11, 0
	s_add_u32 s100, s2, 1
	s_mul_i32 s100, s100, 3
	s_mov_b64 exec, 1
	v_mov_b32_e32 v132, 0

; #define LAS __attribute__((address_space(3)))
; __device__ __forceinline__ int opaque_tid(int wv) { asm volatile("" : "+s"(wv)); unsigned z = 0u; asm volatile("" : "+v"(z)); const int l = __builtin_amdgcn_mbcnt_hi(~0u, __builtin_amdgcn_mbcnt_lo(~0u, z)); return (wv << 6) | l; }
; __device__ __forceinline__ void convert_weight(int wv, const float* __restrict__ src, int ldsrc, int Ksrc, bf16_t* dst, int ldd, int koff, int ntn, const float* kscale, int mode, LAS float* tile, int pidx, int pcnt) {
;     const int tid = opaque_tid(wv); const int ntk = Ksrc / 128; const int total = ntn * ntk; const int G = pcnt;
;     const int kk0 = tid >> 4, n4 = (tid & 15) * 4;
;     f32x4 v[4]; float ks[4];
;     auto prefetch = [&](int t) {
;         const int tn = t % ntn, tk = t / ntn; const int n0 = tn * 64, k0 = tk * 128;
;         int scol = n0, nvalid = 64;
;         if (mode == 1) { if (n0 < 5632) scol = n0; else if (n0 < 13312) scol = n0 + 8; else if (n0 == 13312) { scol = 5632; nvalid = 8; } else { scol = 0; nvalid = 0; } }
; #pragma unroll
;         for (int i = 0; i < 4; ++i) { const int kk = kk0 + i * 32; v[i] = (f32x4){0.f, 0.f, 0.f, 0.f};
;             if (n4 < nvalid) v[i] = *(const f32x4*)(src + (size_t)(k0 + kk) * ldsrc + scol + n4);
;             ks[i] = kscale ? kscale[k0 + kk] : 1.0f; }
;     };
;     int t = pidx; int buf = 0;
;     if (t < total) prefetch(t);
; __device__ __forceinline__ void convert_layer(int wv, PP P, int L, int mask, LAS float* tile, int pidx, int pcnt) {
;     ...
;     if (mask & 1) convert_weight(wv, P->w_in + (size_t)L * D * DIN, DIN, D, (bf16_t*)(ws + WS_WIN), D, 0, NZ / 64, P->norm_mix + L * D, 1, tile, pidx, pcnt);
.LBB0_642:
	v_readlane_b32 s4, v254, 30
	v_readlane_b32 s5, v254, 31
	s_and_b64 vcc, exec, s[4:5]
	s_cbranch_vccnz .LBB0_703
	s_mov_b32 s4, s81
	s_movk_i32 s5, 64
	s_cmp_lt_i32 s4, s5
	s_cselect_b64 s[6:7], -1, 0
	s_or_b64 s[6:7], s[82:83], s[6:7]
	s_and_b64 vcc, exec, s[6:7]
	s_cbranch_vccnz .LBB0_703
	s_movk_i32 s5, 64
	s_sub_i32 s22, s4, s5
	s_mov_b64 s[10:11], s[0:1]
	s_mov_b32 s8, s95
	v_mov_b32_e32 v0, v3
	s_cmpk_gt_i32 s22, 0xd3f
	s_cbranch_scc1 .LBB0_702
	v_mbcnt_lo_u32_b32 v10, -1, 0
	v_mbcnt_hi_u32_b32 v10, -1, v10
	v_lshl_or_b32 v10, s95, 6, v10
	v_lshrrev_b32_e32 v11, 4, v10
	v_and_b32_e32 v9, 15, v10
	v_lshlrev_b32_e32 v9, 2, v9
	v_mul_u32_u24_e32 v4, 0x3408, v11
	v_add_u32_e32 v4, v4, v9
	v_lshlrev_b32_e32 v4, 2, v4
	v_lshlrev_b32_e32 v5, 2, v11
	v_mul_u32_u24_e32 v6, 65, v11
	v_add_u32_e32 v6, v6, v9
	v_lshlrev_b32_e32 v6, 2, v6
	v_lshrrev_b32_e32 v7, 3, v10
	v_and_b32_e32 v8, 7, v10
	v_lshlrev_b32_e32 v8, 4, v8
	v_mul_u32_u24_e32 v11, 65, v8
	v_add_u32_e32 v11, v11, v7
	v_lshlrev_b32_e32 v8, 1, v8
	v_mul_u32_u24_e32 v10, 0x1000, v7
	v_add_u32_e32 v8, v10, v8
	v_lshlrev_b32_e32 v7, 2, v11
	s_load_dwordx2 s[4:5], s[0:1], 0x18
	s_load_dwordx2 s[6:7], s[0:1], 0x10
	s_load_dwordx2 s[8:9], s[0:1], 0xa0
	s_waitcnt lgkmcnt(0)
	s_add_u32 s4, s4, 0x6810000
	s_addc_u32 s5, s5, 0
	s_add_u32 s6, s6, 0x2000
	s_addc_u32 s7, s7, 0
	s_add_u32 s8, s8, 0x23100000
	s_addc_u32 s9, s9, 0
	s_mov_b32 s10, s22
	s_mul_hi_u32 s15, s10, 0x13521d0
	s_mul_i32 s14, s15, 212
	s_sub_u32 s14, s10, s14
	s_lshl_b32 s18, s14, 6
	s_mov_b32 s28, 0
	s_cmp_lt_u32 s14, 88
	s_cbranch_scc1 .Lcv1_cp0
	s_add_u32 s18, s18, 8
	s_cmp_lt_u32 s14, 208
	s_cbranch_scc1 .Lcv1_cp0
	s_movk_i32 s18, 0x1600
	s_mov_b32 s28, 1
	s_cmp_eq_u32 s14, 208
	s_cbranch_scc1 .Lcv1_cp0
	s_mov_b32 s18, 0
	s_mov_b32 s28, 2
.Lcv1_cp0:
	s_mul_i32 s19, s15, 0x1a0400
	s_add_u32 s19, s19, s18
	s_lshl_b32 s19, s19, 2
	s_add_u32 s20, s4, s19
	s_addc_u32 s21, s5, 0
	s_lshl_b32 s19, s15, 9
	s_add_u32 s22, s6, s19
	s_addc_u32 s23, s7, 0
	global_load_dwordx4 v[12:15], v4, s[20:21]
	global_load_dword v28, v5, s[22:23]
	s_add_u32 s20, s20, 0x1a0400
	s_addc_u32 s21, s21, 0
	global_load_dwordx4 v[16:19], v4, s[20:21]
	global_load_dword v29, v5, s[22:23] offset:128
	s_add_u32 s20, s20, 0x1a0400
	s_addc_u32 s21, s21, 0
	global_load_dwordx4 v[20:23], v4, s[20:21]
	global_load_dword v30, v5, s[22:23] offset:256
	s_add_u32 s20, s20, 0x1a0400
	s_addc_u32 s21, s21, 0
	global_load_dwordx4 v[24:27], v4, s[20:21]
	global_load_dword v31, v5, s[22:23] offset:384
	s_add_u32 s11, s10, 192
	s_cmp_lt_u32 s11, 3392
	s_cbranch_scc0 .Lcv1_p1n
	s_mul_hi_u32 s15, s11, 0x13521d0
	s_mul_i32 s14, s15, 212
	s_sub_u32 s14, s11, s14
	s_lshl_b32 s18, s14, 6
	s_mov_b32 s29, 0
	s_cmp_lt_u32 s14, 88
	s_cbranch_scc1 .Lcv1_cp1
	s_add_u32 s18, s18, 8
	s_cmp_lt_u32 s14, 208
	s_cbranch_scc1 .Lcv1_cp1
	s_movk_i32 s18, 0x1600
	s_mov_b32 s29, 1
	s_cmp_eq_u32 s14, 208
	s_cbranch_scc1 .Lcv1_cp1
	s_mov_b32 s18, 0
	s_mov_b32 s29, 2

; #define LAS __attribute__((address_space(3)))
; __device__ __forceinline__ void lds_barrier() { asm volatile("s_waitcnt lgkmcnt(0)" ::: "memory"); __builtin_amdgcn_s_barrier(); asm volatile("" ::: "memory"); }
; __device__ __forceinline__ void convert_weight(int wv, const float* __restrict__ src, int ldsrc, int Ksrc, bf16_t* dst, int ldd, int koff, int ntn, const float* kscale, int mode, LAS float* tile, int pidx, int pcnt) {
;     ...
;         for (int i = 0; i < 4; ++i) { const int kk = kk0 + i * 32; v[i] = (f32x4){0.f, 0.f, 0.f, 0.f};
;             if (n4 < nvalid) v[i] = *(const f32x4*)(src + (size_t)(k0 + kk) * ldsrc + scol + n4);
;             ks[i] = kscale ? kscale[k0 + kk] : 1.0f; }
;     };
;     int t = pidx; int buf = 0;
;     if (t < total) prefetch(t);
;     for (; t < total; t += G) {
;         LAS float* tl = tile + buf * (128 * 65);
; #pragma unroll
;         for (int i = 0; i < 4; ++i) { const int kk = kk0 + i * 32;
;             tl[kk * 65 + n4 + 0] = v[i][0] * ks[i]; tl[kk * 65 + n4 + 1] = v[i][1] * ks[i]; tl[kk * 65 + n4 + 2] = v[i][2] * ks[i]; tl[kk * 65 + n4 + 3] = v[i][3] * ks[i]; }
;         lds_barrier();
;         const int tn = t % ntn, tk = t / ntn; const int n0 = tn * 64, k0 = tk * 128;
;         if (t + G < total) prefetch(t + G);
.Lcv1_ma:
	v_mul_f32_e32 v12, v12, v28
	v_mul_f32_e32 v13, v13, v28
	v_mul_f32_e32 v14, v14, v28
	v_mul_f32_e32 v15, v15, v28
	v_mul_f32_e32 v16, v16, v29
	v_mul_f32_e32 v17, v17, v29
	v_mul_f32_e32 v18, v18, v29
	v_mul_f32_e32 v19, v19, v29
	v_mul_f32_e32 v20, v20, v30
	v_mul_f32_e32 v21, v21, v30
	v_mul_f32_e32 v22, v22, v30
	v_mul_f32_e32 v23, v23, v30
	v_mul_f32_e32 v24, v24, v31
	v_mul_f32_e32 v25, v25, v31
	v_mul_f32_e32 v26, v26, v31
	v_mul_f32_e32 v27, v27, v31
	ds_write_b32 v6, v12 offset:0
	ds_write_b32 v6, v13 offset:4
	ds_write_b32 v6, v14 offset:8
	ds_write_b32 v6, v15 offset:12
	ds_write_b32 v6, v16 offset:8320
	ds_write_b32 v6, v17 offset:8324
	ds_write_b32 v6, v18 offset:8328
	ds_write_b32 v6, v19 offset:8332
	ds_write_b32 v6, v20 offset:16640
	ds_write_b32 v6, v21 offset:16644
	ds_write_b32 v6, v22 offset:16648
	ds_write_b32 v6, v23 offset:16652
	ds_write_b32 v6, v24 offset:24960
	ds_write_b32 v6, v25 offset:24964
	ds_write_b32 v6, v26 offset:24968
	ds_write_b32 v6, v27 offset:24972
	s_waitcnt lgkmcnt(0)
	s_barrier
	s_add_u32 s11, s10, 384
	s_mov_b32 s27, 0
	s_cmp_lt_u32 s11, 3392
	s_cbranch_scc0 .Lcv1_na
	s_mov_b32 s27, 1
	s_mul_hi_u32 s15, s11, 0x13521d0
	s_mul_i32 s14, s15, 212
	s_sub_u32 s14, s11, s14
	s_lshl_b32 s18, s14, 6
	s_mov_b32 s28, 0
	s_cmp_lt_u32 s14, 88
	s_cbranch_scc1 .Lcv1_ca
	s_add_u32 s18, s18, 8
	s_cmp_lt_u32 s14, 208
	s_cbranch_scc1 .Lcv1_ca
	s_movk_i32 s18, 0x1600
	s_mov_b32 s28, 1
	s_cmp_eq_u32 s14, 208
	s_cbranch_scc1 .Lcv1_ca
	s_mov_b32 s18, 0
	s_mov_b32 s28, 2

; __device__ __forceinline__ unsigned pack2(float lo, float hi) { unsigned r; asm("v_cvt_pk_bf16_f32 %0, %1, %2" : "=v"(r) : "v"(lo), "v"(hi)); return r; }
; __device__ __forceinline__ void convert_weight(int wv, const float* __restrict__ src, int ldsrc, int Ksrc, bf16_t* dst, int ldd, int koff, int ntn, const float* kscale, int mode, LAS float* tile, int pidx, int pcnt) {
;     ...
;         const int tn = t % ntn, tk = t / ntn; const int n0 = tn * 64, k0 = tk * 128;
;         if (t + G < total) prefetch(t + G);
;         { const int n = tid >> 3, k16 = (tid & 7) * 16; u32x4 w0, w1;
;           w0.x = pack2(tl[(k16 + 0) * 65 + n], tl[(k16 + 1) * 65 + n]); w0.y = pack2(tl[(k16 + 2) * 65 + n], tl[(k16 + 3) * 65 + n]);
;           w0.z = pack2(tl[(k16 + 4) * 65 + n], tl[(k16 + 5) * 65 + n]); w0.w = pack2(tl[(k16 + 6) * 65 + n], tl[(k16 + 7) * 65 + n]);
;           w1.x = pack2(tl[(k16 + 8) * 65 + n], tl[(k16 + 9) * 65 + n]); w1.y = pack2(tl[(k16 + 10) * 65 + n], tl[(k16 + 11) * 65 + n]);
;           w1.z = pack2(tl[(k16 + 12) * 65 + n], tl[(k16 + 13) * 65 + n]); w1.w = pack2(tl[(k16 + 14) * 65 + n], tl[(k16 + 15) * 65 + n]);
;           bf16_t* dp = dst + (size_t)(n0 + n) * ldd + koff + k0 + k16; *(u32x4*)dp = w0; *(u32x4*)(dp + 8) = w1; }
;         buf ^= 1;
.Lcv1_na:
	ds_read_b32 v52, v7 offset:0
	ds_read_b32 v53, v7 offset:260
	ds_read_b32 v54, v7 offset:520
	ds_read_b32 v55, v7 offset:780
	ds_read_b32 v56, v7 offset:1040
	ds_read_b32 v57, v7 offset:1300
	ds_read_b32 v58, v7 offset:1560
	ds_read_b32 v59, v7 offset:1820
	ds_read_b32 v60, v7 offset:2080
	ds_read_b32 v61, v7 offset:2340
	ds_read_b32 v62, v7 offset:2600
	ds_read_b32 v63, v7 offset:2860
	ds_read_b32 v64, v7 offset:3120
	ds_read_b32 v65, v7 offset:3380
	ds_read_b32 v66, v7 offset:3640
	ds_read_b32 v67, v7 offset:3900
	s_mul_hi_u32 s15, s10, 0x13521d0
	s_mul_i32 s14, s15, 212
	s_sub_u32 s14, s10, s14
	s_mul_i32 s14, s14, 0x40000
	s_lshl_b32 s15, s15, 8
	s_add_u32 s14, s14, s15
	s_add_u32 s24, s8, s14
	s_addc_u32 s25, s9, 0
	s_waitcnt lgkmcnt(14)
	v_cvt_pk_bf16_f32 v68, v52, v53
	s_waitcnt lgkmcnt(12)
	v_cvt_pk_bf16_f32 v69, v54, v55
	s_waitcnt lgkmcnt(10)
	v_cvt_pk_bf16_f32 v70, v56, v57
	s_waitcnt lgkmcnt(8)
	v_cvt_pk_bf16_f32 v71, v58, v59
	s_waitcnt lgkmcnt(6)
	v_cvt_pk_bf16_f32 v72, v60, v61
	s_waitcnt lgkmcnt(4)
	v_cvt_pk_bf16_f32 v73, v62, v63
	s_waitcnt lgkmcnt(2)
	v_cvt_pk_bf16_f32 v74, v64, v65
	s_waitcnt lgkmcnt(0)
	v_cvt_pk_bf16_f32 v75, v66, v67
	global_store_dwordx4 v8, v[68:71], s[24:25]
	global_store_dwordx4 v8, v[72:75], s[24:25] offset:16
	s_add_u32 s10, s10, 192
	s_cmp_lt_u32 s10, 3392
	s_cbranch_scc0 .Lcv1_end
	s_cmp_eq_u32 s27, 0
	s_cbranch_scc1 .Lcv1_wa
	s_waitcnt vmcnt(10)
	s_branch .Lcv1_xa

; #define LAS __attribute__((address_space(3)))
; __device__ __forceinline__ void lds_barrier() { asm volatile("s_waitcnt lgkmcnt(0)" ::: "memory"); __builtin_amdgcn_s_barrier(); asm volatile("" ::: "memory"); }
; __device__ __forceinline__ void convert_weight(int wv, const float* __restrict__ src, int ldsrc, int Ksrc, bf16_t* dst, int ldd, int koff, int ntn, const float* kscale, int mode, LAS float* tile, int pidx, int pcnt) {
;     ...
;         for (int i = 0; i < 4; ++i) { const int kk = kk0 + i * 32; v[i] = (f32x4){0.f, 0.f, 0.f, 0.f};
;             if (n4 < nvalid) v[i] = *(const f32x4*)(src + (size_t)(k0 + kk) * ldsrc + scol + n4);
;             ks[i] = kscale ? kscale[k0 + kk] : 1.0f; }
;     };
;     int t = pidx; int buf = 0;
;     if (t < total) prefetch(t);
;     for (; t < total; t += G) {
;         LAS float* tl = tile + buf * (128 * 65);
; #pragma unroll
;         for (int i = 0; i < 4; ++i) { const int kk = kk0 + i * 32;
;             tl[kk * 65 + n4 + 0] = v[i][0] * ks[i]; tl[kk * 65 + n4 + 1] = v[i][1] * ks[i]; tl[kk * 65 + n4 + 2] = v[i][2] * ks[i]; tl[kk * 65 + n4 + 3] = v[i][3] * ks[i]; }
;         lds_barrier();
;         const int tn = t % ntn, tk = t / ntn; const int n0 = tn * 64, k0 = tk * 128;
;         if (t + G < total) prefetch(t + G);
.Lcv1_mb:
	v_mul_f32_e32 v32, v32, v48
	v_mul_f32_e32 v33, v33, v48
	v_mul_f32_e32 v34, v34, v48
	v_mul_f32_e32 v35, v35, v48
	v_mul_f32_e32 v36, v36, v49
	v_mul_f32_e32 v37, v37, v49
	v_mul_f32_e32 v38, v38, v49
	v_mul_f32_e32 v39, v39, v49
	v_mul_f32_e32 v40, v40, v50
	v_mul_f32_e32 v41, v41, v50
	v_mul_f32_e32 v42, v42, v50
	v_mul_f32_e32 v43, v43, v50
	v_mul_f32_e32 v44, v44, v51
	v_mul_f32_e32 v45, v45, v51
	v_mul_f32_e32 v46, v46, v51
	v_mul_f32_e32 v47, v47, v51
	ds_write_b32 v6, v32 offset:33280
	ds_write_b32 v6, v33 offset:33284
	ds_write_b32 v6, v34 offset:33288
	ds_write_b32 v6, v35 offset:33292
	ds_write_b32 v6, v36 offset:41600
	ds_write_b32 v6, v37 offset:41604
	ds_write_b32 v6, v38 offset:41608
	ds_write_b32 v6, v39 offset:41612
	ds_write_b32 v6, v40 offset:49920
	ds_write_b32 v6, v41 offset:49924
	ds_write_b32 v6, v42 offset:49928
	ds_write_b32 v6, v43 offset:49932
	ds_write_b32 v6, v44 offset:58240
	ds_write_b32 v6, v45 offset:58244
	ds_write_b32 v6, v46 offset:58248
	ds_write_b32 v6, v47 offset:58252
	s_waitcnt lgkmcnt(0)
	s_barrier
	s_add_u32 s11, s10, 384
	s_mov_b32 s27, 0
	s_cmp_lt_u32 s11, 3392
	s_cbranch_scc0 .Lcv1_nb
	s_mov_b32 s27, 1
	s_mul_hi_u32 s15, s11, 0x13521d0
	s_mul_i32 s14, s15, 212
	s_sub_u32 s14, s11, s14
	s_lshl_b32 s18, s14, 6
	s_mov_b32 s29, 0
	s_cmp_lt_u32 s14, 88
	s_cbranch_scc1 .Lcv1_cb
	s_add_u32 s18, s18, 8
	s_cmp_lt_u32 s14, 208
	s_cbranch_scc1 .Lcv1_cb
	s_movk_i32 s18, 0x1600
	s_mov_b32 s29, 1
	s_cmp_eq_u32 s14, 208
	s_cbranch_scc1 .Lcv1_cb
	s_mov_b32 s18, 0
	s_mov_b32 s29, 2

; __device__ __forceinline__ unsigned pack2(float lo, float hi) { unsigned r; asm("v_cvt_pk_bf16_f32 %0, %1, %2" : "=v"(r) : "v"(lo), "v"(hi)); return r; }
; __device__ __forceinline__ void convert_weight(int wv, const float* __restrict__ src, int ldsrc, int Ksrc, bf16_t* dst, int ldd, int koff, int ntn, const float* kscale, int mode, LAS float* tile, int pidx, int pcnt) {
;     ...
;         const int tn = t % ntn, tk = t / ntn; const int n0 = tn * 64, k0 = tk * 128;
;         if (t + G < total) prefetch(t + G);
;         { const int n = tid >> 3, k16 = (tid & 7) * 16; u32x4 w0, w1;
;           w0.x = pack2(tl[(k16 + 0) * 65 + n], tl[(k16 + 1) * 65 + n]); w0.y = pack2(tl[(k16 + 2) * 65 + n], tl[(k16 + 3) * 65 + n]);
;           w0.z = pack2(tl[(k16 + 4) * 65 + n], tl[(k16 + 5) * 65 + n]); w0.w = pack2(tl[(k16 + 6) * 65 + n], tl[(k16 + 7) * 65 + n]);
;           w1.x = pack2(tl[(k16 + 8) * 65 + n], tl[(k16 + 9) * 65 + n]); w1.y = pack2(tl[(k16 + 10) * 65 + n], tl[(k16 + 11) * 65 + n]);
;           w1.z = pack2(tl[(k16 + 12) * 65 + n], tl[(k16 + 13) * 65 + n]); w1.w = pack2(tl[(k16 + 14) * 65 + n], tl[(k16 + 15) * 65 + n]);
;           bf16_t* dp = dst + (size_t)(n0 + n) * ldd + koff + k0 + k16; *(u32x4*)dp = w0; *(u32x4*)(dp + 8) = w1; }
;         buf ^= 1;
.Lcv1_nb:
	ds_read_b32 v52, v7 offset:33280
	ds_read_b32 v53, v7 offset:33540
	ds_read_b32 v54, v7 offset:33800
	ds_read_b32 v55, v7 offset:34060
	ds_read_b32 v56, v7 offset:34320
	ds_read_b32 v57, v7 offset:34580
	ds_read_b32 v58, v7 offset:34840
	ds_read_b32 v59, v7 offset:35100
	ds_read_b32 v60, v7 offset:35360
	ds_read_b32 v61, v7 offset:35620
	ds_read_b32 v62, v7 offset:35880
	ds_read_b32 v63, v7 offset:36140
	ds_read_b32 v64, v7 offset:36400
	ds_read_b32 v65, v7 offset:36660
	ds_read_b32 v66, v7 offset:36920
	ds_read_b32 v67, v7 offset:37180
	s_mul_hi_u32 s15, s10, 0x13521d0
	s_mul_i32 s14, s15, 212
	s_sub_u32 s14, s10, s14
	s_mul_i32 s14, s14, 0x40000
	s_lshl_b32 s15, s15, 8
	s_add_u32 s14, s14, s15
	s_add_u32 s24, s8, s14
	s_addc_u32 s25, s9, 0
	s_waitcnt lgkmcnt(14)
	v_cvt_pk_bf16_f32 v68, v52, v53
	s_waitcnt lgkmcnt(12)
	v_cvt_pk_bf16_f32 v69, v54, v55
	s_waitcnt lgkmcnt(10)
	v_cvt_pk_bf16_f32 v70, v56, v57
	s_waitcnt lgkmcnt(8)
	v_cvt_pk_bf16_f32 v71, v58, v59
	s_waitcnt lgkmcnt(6)
	v_cvt_pk_bf16_f32 v72, v60, v61
	s_waitcnt lgkmcnt(4)
	v_cvt_pk_bf16_f32 v73, v62, v63
	s_waitcnt lgkmcnt(2)
	v_cvt_pk_bf16_f32 v74, v64, v65
	s_waitcnt lgkmcnt(0)
	v_cvt_pk_bf16_f32 v75, v66, v67
	global_store_dwordx4 v8, v[68:71], s[24:25]
	global_store_dwordx4 v8, v[72:75], s[24:25] offset:16
	s_add_u32 s10, s10, 192
	s_cmp_lt_u32 s10, 3392
	s_cbranch_scc0 .Lcv1_end
	s_cmp_eq_u32 s27, 0
	s_cbranch_scc1 .Lcv1_wb
	s_waitcnt vmcnt(10)
	s_branch .Lcv1_xb

; #define LAS __attribute__((address_space(3)))
; __device__ __forceinline__ int opaque_tid(int wv) { asm volatile("" : "+s"(wv)); unsigned z = 0u; asm volatile("" : "+v"(z)); const int l = __builtin_amdgcn_mbcnt_hi(~0u, __builtin_amdgcn_mbcnt_lo(~0u, z)); return (wv << 6) | l; }
; __device__ __forceinline__ void convert_weight(int wv, const float* __restrict__ src, int ldsrc, int Ksrc, bf16_t* dst, int ldd, int koff, int ntn, const float* kscale, int mode, LAS float* tile, int pidx, int pcnt) {
;     const int tid = opaque_tid(wv); const int ntk = Ksrc / 128; const int total = ntn * ntk; const int G = pcnt;
;     const int kk0 = tid >> 4, n4 = (tid & 15) * 4;
;     f32x4 v[4]; float ks[4];
;     auto prefetch = [&](int t) {
;         const int tn = t % ntn, tk = t / ntn; const int n0 = tn * 64, k0 = tk * 128;
;         int scol = n0, nvalid = 64;
;         if (mode == 1) { if (n0 < 5632) scol = n0; else if (n0 < 13312) scol = n0 + 8; else if (n0 == 13312) { scol = 5632; nvalid = 8; } else { scol = 0; nvalid = 0; } }
; #pragma unroll
;         for (int i = 0; i < 4; ++i) { const int kk = kk0 + i * 32; v[i] = (f32x4){0.f, 0.f, 0.f, 0.f};
;             if (n4 < nvalid) v[i] = *(const f32x4*)(src + (size_t)(k0 + kk) * ldsrc + scol + n4);
;             ks[i] = kscale ? kscale[k0 + kk] : 1.0f; }
;     };
;     int t = pidx; int buf = 0;
;     if (t < total) prefetch(t);
; __device__ __forceinline__ void convert_layer(int wv, PP P, int L, int mask, LAS float* tile, int pidx, int pcnt) {
;     ...
;     if (mask & 8) convert_weight(wv, P->w_up + (size_t)L * D * NUP, NUP, D, (bf16_t*)(dob + DO_WUP), D, 0, NUP / 64, P->norm_ffn + L * D, 0, tile, pidx, pcnt);
.LBB0_945:
	v_readlane_b32 s4, v254, 30
	v_readlane_b32 s5, v254, 31
	s_and_b64 vcc, exec, s[4:5]
	s_cbranch_vccnz .LBB0_970
	s_mov_b32 s4, s81
	s_movk_i32 s5, 64
	s_cmp_lt_i32 s4, s5
	s_cselect_b64 s[6:7], -1, 0
	s_or_b64 s[6:7], s[82:83], s[6:7]
	s_and_b64 vcc, exec, s[6:7]
	s_cbranch_vccnz .LBB0_970
	s_movk_i32 s5, 64
	s_sub_i32 s16, s4, s5
	s_mov_b64 s[10:11], s[0:1]
	s_mov_b32 s4, s95
	v_mov_b32_e32 v0, v3
	s_cmpk_gt_i32 s16, 0xaff
	s_cbranch_scc1 .LBB0_969
	v_mbcnt_lo_u32_b32 v10, -1, 0
	v_mbcnt_hi_u32_b32 v10, -1, v10
	v_lshl_or_b32 v10, s95, 6, v10
	v_lshrrev_b32_e32 v11, 4, v10
	v_and_b32_e32 v9, 15, v10
	v_lshlrev_b32_e32 v9, 2, v9
	v_mul_u32_u24_e32 v4, 0x2c00, v11
	v_add_u32_e32 v4, v4, v9
	v_lshlrev_b32_e32 v4, 2, v4
	v_lshlrev_b32_e32 v5, 2, v11
	v_mul_u32_u24_e32 v6, 65, v11
	v_add_u32_e32 v6, v6, v9
	v_lshlrev_b32_e32 v6, 2, v6
	v_lshrrev_b32_e32 v7, 3, v10
	v_and_b32_e32 v8, 7, v10
	v_lshlrev_b32_e32 v8, 4, v8
	v_mul_u32_u24_e32 v11, 65, v8
	v_add_u32_e32 v11, v11, v7
	v_lshlrev_b32_e32 v8, 1, v8
	v_mul_u32_u24_e32 v10, 0x1000, v7
	v_add_u32_e32 v8, v10, v8
	v_lshlrev_b32_e32 v7, 2, v11
	s_load_dwordx2 s[4:5], s[0:1], 0x70
	s_load_dwordx2 s[6:7], s[0:1], 0x68
	s_load_dwordx2 s[8:9], s[0:1], 0x98
	s_waitcnt lgkmcnt(0)
	s_add_u32 s4, s4, 0x5800000
	s_addc_u32 s5, s5, 0
	s_add_u32 s6, s6, 0x2000
	s_addc_u32 s7, s7, 0
	s_add_u32 s8, s8, 0x5200000
	s_addc_u32 s9, s9, 0
	s_mov_b32 s10, s16
	s_mul_hi_u32 s15, s10, 0x1745d18
	s_mul_i32 s14, s15, 176
	s_sub_u32 s14, s10, s14
	s_lshl_b32 s18, s14, 6
	s_mov_b32 s28, 0
	s_mul_i32 s19, s15, 0x160000
	s_add_u32 s19, s19, s18
	s_lshl_b32 s19, s19, 2
	s_add_u32 s20, s4, s19
	s_addc_u32 s21, s5, 0
	s_lshl_b32 s19, s15, 9
	s_add_u32 s22, s6, s19
	s_addc_u32 s23, s7, 0
	global_load_dwordx4 v[12:15], v4, s[20:21]
	global_load_dword v28, v5, s[22:23]
	s_add_u32 s20, s20, 0x160000
	s_addc_u32 s21, s21, 0
	global_load_dwordx4 v[16:19], v4, s[20:21]
	global_load_dword v29, v5, s[22:23] offset:128
	s_add_u32 s20, s20, 0x160000
	s_addc_u32 s21, s21, 0
	global_load_dwordx4 v[20:23], v4, s[20:21]
	global_load_dword v30, v5, s[22:23] offset:256
	s_add_u32 s20, s20, 0x160000
	s_addc_u32 s21, s21, 0
	global_load_dwordx4 v[24:27], v4, s[20:21]
	global_load_dword v31, v5, s[22:23] offset:384
	s_add_u32 s11, s10, 192
	s_cmp_lt_u32 s11, 2816
	s_cbranch_scc0 .Lcv2_p1n
	s_mul_hi_u32 s15, s11, 0x1745d18
	s_mul_i32 s14, s15, 176
	s_sub_u32 s14, s11, s14
	s_lshl_b32 s18, s14, 6
	s_mov_b32 s29, 0
	s_mul_i32 s19, s15, 0x160000
	s_add_u32 s19, s19, s18
	s_lshl_b32 s19, s19, 2
	s_add_u32 s20, s4, s19
	s_addc_u32 s21, s5, 0
	s_lshl_b32 s19, s15, 9
	s_add_u32 s22, s6, s19
	s_addc_u32 s23, s7, 0
	global_load_dwordx4 v[32:35], v4, s[20:21]
	global_load_dword v48, v5, s[22:23]
	s_add_u32 s20, s20, 0x160000
	s_addc_u32 s21, s21, 0
	global_load_dwordx4 v[36:39], v4, s[20:21]
	global_load_dword v49, v5, s[22:23] offset:128
	s_add_u32 s20, s20, 0x160000
	s_addc_u32 s21, s21, 0
	global_load_dwordx4 v[40:43], v4, s[20:21]
	global_load_dword v50, v5, s[22:23] offset:256
	s_add_u32 s20, s20, 0x160000
	s_addc_u32 s21, s21, 0
	global_load_dwordx4 v[44:47], v4, s[20:21]
	global_load_dword v51, v5, s[22:23] offset:384
	s_waitcnt vmcnt(8)
	s_branch .Lcv2_loop
